# XCD-local barriers (11 of 21) with a runtime check that workgroups of one logical XCD share a physical XCD (falls back to grid-wide barriers otherwise); hmat and p4b items remapped to the owning XCD
# baseline (speedup 1.0000x reference)
.LBB0_19:
	s_load_dwordx16 s[0:15], s[86:87], 0x0
	s_cmp_gt_i32 s66, 0
	s_waitcnt lgkmcnt(0)
	v_writelane_b32 v251, s0, 39
	s_nop 1
	v_writelane_b32 v251, s1, 40
	v_writelane_b32 v251, s2, 41
	v_writelane_b32 v251, s3, 42
	v_writelane_b32 v251, s4, 43
	v_writelane_b32 v251, s5, 44
	v_writelane_b32 v251, s6, 45
	v_writelane_b32 v251, s7, 46
	v_writelane_b32 v251, s8, 47
	v_writelane_b32 v251, s9, 48
	v_writelane_b32 v251, s10, 49
	v_writelane_b32 v251, s11, 50
	v_writelane_b32 v251, s12, 51
	v_writelane_b32 v251, s13, 52
	v_writelane_b32 v251, s14, 53
	v_writelane_b32 v251, s15, 54
	s_cselect_b64 s[2:3], -1, 0
	s_cmp_lt_i32 s67, 1
	s_cselect_b64 s[4:5], -1, 0
	s_or_b64 s[2:3], s[2:3], s[4:5]
	s_and_b64 vcc, exec, s[2:3]
	v_writelane_b32 v251, s66, 55
	s_nop 1
	v_writelane_b32 v251, s67, 56
	s_cbranch_vccnz .LBB0_135
	s_cmpk_lt_u32 s78, 8
	s_cbranch_scc0 .Llb_nopub
	v_readlane_b32 s0, v251, 2
	s_lshl_b32 s1, s78, 2
	s_add_i32 s1, s1, 0x7fc00
	v_mov_b32_e32 v132, s1
	v_mov_b32_e32 v133, s0
	global_store_dword v132, v133, s[30:31]
.Llb_nopub:
	v_readlane_b32 s0, v251, 5
	s_mov_b32 s33, s78
	s_cmpk_gt_i32 s78, 0xb40
	v_readlane_b32 s1, v251, 6
	v_readlane_b32 s0, v251, 2
	s_cbranch_scc1 .LBB0_85
	s_add_u32 s0, s30, 0x83e00
	s_addc_u32 s1, s31, 0
	v_writelane_b32 v251, s0, 57
	s_add_u32 s3, s30, 0x93e00
	s_load_dwordx16 s[36:51], s[86:87], 0x0
	v_writelane_b32 v251, s1, 58
	s_addc_u32 s0, s31, 0
	v_writelane_b32 v251, s0, 59
	s_add_u32 s0, s30, 0x113e00
	v_writelane_b32 v251, s0, 61
	s_addc_u32 s0, s31, 0
	v_writelane_b32 v251, s0, 63
	s_add_u32 s0, s30, 0x1993e00
	s_addc_u32 s1, s31, 0
	v_writelane_b32 v250, s0, 1
	s_mov_b32 s8, 0x54442d18
	s_mov_b32 s26, 0x6dc9c883
	v_writelane_b32 v250, s1, 2
	s_add_u32 s0, s30, 0xb93e00
	s_addc_u32 s1, s31, 0
	v_writelane_b32 v250, s0, 3
	s_mov_b32 s10, 0x33145c00
	s_mov_b32 s70, 0x252049c0
	v_writelane_b32 v250, s1, 4
	s_add_u32 s0, s30, 0x993e00
	v_writelane_b32 v250, s0, 5
	s_addc_u32 s0, s31, 0
	s_add_u32 s65, s30, 0x593e00
	s_addc_u32 s66, s31, 0
	s_add_u32 s14, s30, 0x7fe00
	s_addc_u32 s15, s31, 0
	v_writelane_b32 v250, s0, 6
	s_add_u32 s0, s30, 0x193e04
	v_writelane_b32 v250, s0, 22
	s_addc_u32 s0, s31, 0
	s_lshl_b32 s2, s33, 6
	s_add_i32 s67, s2, 0xffff3fc0
	s_add_i32 s84, s33, 0xfffffcff
	s_lshl_b32 s85, s64, 6
	v_writelane_b32 v250, s0, 24
	s_waitcnt lgkmcnt(0)
	s_add_u32 s0, s44, 8
	v_writelane_b32 v250, s0, 26
	s_addc_u32 s0, s45, 0
	v_writelane_b32 v250, s0, 28
	s_mov_b32 s1, 0x3fa55555
	s_mov_b32 s76, 0x46cc5e42
	s_mov_b32 s78, 0xf9a43bb8
	s_mov_b32 s74, 0x55555555
	v_writelane_b32 v250, s0, 30
	s_mov_b32 s16, 0
	s_mov_b32 s22, 0
	s_mov_b32 s72, 0
	s_mov_b32 s91, s33
	v_mov_b32_e32 v20, 0
	s_mov_b32 s9, 0xbff921fb
	s_mov_b32 s27, 0x3fe45f30
	s_mov_b32 s11, 0xbc91a626
	s_mov_b32 s71, 0xb97b839a
	s_mov_b32 s77, 0xbda907db
	s_mov_b32 s79, 0x3de5e0b2
	s_mov_b32 s75, 0xbfc55555
	v_mov_b32_e32 v22, 0xfca7ab0c
	v_mov_b32_e32 v23, 0x3e928af3
	v_mov_b32_e32 v24, 0x623fde64
	v_mov_b32_e32 v25, 0x3ec71dee
	v_mov_b32_e32 v26, 0x7c89e6b0
	v_mov_b32_e32 v27, 0x3efa0199
	v_mov_b32_e32 v28, 0x14761f6e
	v_mov_b32_e32 v29, 0x3f2a01a0
	v_mov_b32_e32 v30, 0x1852b7b0
	v_mov_b32_e32 v31, 0x3f56c16c
	v_mov_b32_e32 v32, 0x11122322
	v_mov_b32_e32 v35, 0x3f811111
	v_mov_b32_e32 v36, 0x555502a1
	v_mov_b32_e32 v39, 0x3fa55555
	v_mov_b32_e32 v40, 0x55555511
	v_mov_b32_e32 v41, 0x3fc55555
	v_mov_b32_e32 v42, 11
	v_mov_b32_e32 v43, 0x3fe00000
	v_mov_b32_e32 v80, 0x7ff00000
	v_mov_b32_e32 v81, 0x40100000
	v_mov_b32_e32 v82, 0x3ff00000
	v_mov_b32_e32 v83, 0x7ff80000
	v_mov_b32_e32 v84, 0x40c38800
	v_mov_b32_e32 v44, 0x968915a9
	v_mov_b32_e32 v45, 0x3fba6564
	v_mov_b32_e32 v46, 0x3abe935a
	v_mov_b32_e32 v47, 0x3fbe25e4
	v_mov_b32_e32 v48, 0x47e6c9c2
	v_mov_b32_e32 v49, 0x3fc110ef
	v_mov_b32_e32 v50, 0xcfa74449
	v_mov_b32_e32 v51, 0x3fc3b13b
	v_mov_b32_e32 v52, 0x71bf3c30
	v_mov_b32_e32 v53, 0x3fc745d1
	v_mov_b32_e32 v54, 0x1c7792ce
	v_mov_b32_e32 v55, 0x3fcc71c7
	v_mov_b32_e32 v56, 0x924920da
	v_mov_b32_e32 v57, 0x3fd24924
	v_mov_b32_e32 v58, 0x9999999c
	v_mov_b32_e32 v59, 0x3fd99999
	v_mov_b32_e32 v60, 0x9037ab78
	v_mov_b32_e32 v61, 0x3e21eeb6
	v_mov_b32_e32 v62, 0xa17f65f6
	v_mov_b32_e32 v63, 0xbe927e4f
	v_mov_b32_e32 v64, 0x19f4ec90
	v_mov_b32_e32 v65, 0x3efa01a0
	v_mov_b32_e32 v66, 0x16c16967
	v_mov_b32_e32 v67, 0xbf56c16c
	v_mov_b32_e32 v38, 0x55555555
	v_mov_b32_e32 v68, 0xb42fdfa7
	v_mov_b32_e32 v69, 0xbe5ae600
	v_mov_b32_e32 v70, 0x796cde01
	v_mov_b32_e32 v71, 0x3ec71de3
	v_mov_b32_e32 v72, 0x19e83e5c
	v_mov_b32_e32 v73, 0xbf2a01a0
	v_mov_b32_e32 v34, 0x11110bb3
	v_mov_b32_e32 v85, 0x6050400
	v_mov_b32_e32 v86, 0x1800000
	s_movk_i32 s88, 0xff80
	s_brev_b32 s89, 1
	s_movk_i32 s90, 0x1f8
	s_movk_i32 s92, 0x7000
	s_movk_i32 s93, 0x2000
	s_movk_i32 s94, 0x6000
	s_mov_b32 s95, 0xc000
	s_mov_b32 s96, 0x12000
	s_movk_i32 s97, 0x204
	s_mov_b32 s2, s33
	s_mov_b32 s35, 0
	v_writelane_b32 v250, s1, 31
	s_mov_b32 s17, 0x41d00000
	s_mov_b32 s23, 0x7b000000
	s_mov_b32 s73, 0x7ff00000
	s_mov_b32 s25, 0x3ff921fb
	s_mov_b32 s69, 0x3c91a626
	s_mov_b32 s12, 0x33145c07
	s_mov_b32 s19, 0x3fe55555
	s_mov_b32 s21, 0x3fe62e42
	s_mov_b32 s1, 0x3c7abc9e
	s_mov_b32 s81, 0xbfe55555
	s_branch .LBB0_24

.LBB0_135:
	s_mov_b32 s2, 1
	v_writelane_b32 v250, s2, 60
	s_and_b32 s2, s78, 7
	s_lshl_b32 s2, s2, 2
	s_add_i32 s2, s2, 0x7fc00
	v_mov_b32_e32 v132, s2
	global_load_dword v133, v132, s[30:31] sc1
	v_readlane_b32 s2, v251, 2
	s_waitcnt vmcnt(0)
	v_readfirstlane_b32 s3, v133
	s_cmp_lg_u32 s3, s2
	s_cselect_b32 s5, 1, 0
	s_cmpk_lg_i32 s64, 0x200
	s_cselect_b32 s4, 1, 0
	s_or_b32 s5, s5, s4
	s_cmp_eq_u32 s5, 0
	s_cbranch_scc1 .Llb_ok
	s_mov_b64 s[4:5], exec
	v_readlane_b32 s2, v251, 3
	v_readlane_b32 s3, v251, 4
	s_and_b64 s[2:3], s[4:5], s[2:3]
	s_mov_b64 exec, s[2:3]
	s_cbranch_execz .Llb_rep_done
	v_mov_b32_e32 v132, 0x7fd00
	v_mov_b32_e32 v133, 1
	global_atomic_add v132, v133, s[30:31]
	global_atomic_add v132, v133, s[30:31] offset:4
	global_atomic_add v132, v133, s[30:31] offset:8
	global_atomic_add v132, v133, s[30:31] offset:12
	global_atomic_add v132, v133, s[30:31] offset:16
	global_atomic_add v132, v133, s[30:31] offset:20
	global_atomic_add v132, v133, s[30:31] offset:24
	global_atomic_add v132, v133, s[30:31] offset:28
	global_atomic_add v132, v133, s[30:31] offset:32
	global_atomic_add v132, v133, s[30:31] offset:36
	global_atomic_add v132, v133, s[30:31] offset:40
	global_atomic_add v132, v133, s[30:31] offset:44
	global_atomic_add v132, v133, s[30:31] offset:48
	global_atomic_add v132, v133, s[30:31] offset:52
	global_atomic_add v132, v133, s[30:31] offset:56
	global_atomic_add v132, v133, s[30:31] offset:60
	global_atomic_add v132, v133, s[30:31] offset:64
	global_atomic_add v132, v133, s[30:31] offset:68
	global_atomic_add v132, v133, s[30:31] offset:72
	global_atomic_add v132, v133, s[30:31] offset:76
	global_atomic_add v132, v133, s[30:31] offset:80
	global_atomic_add v132, v133, s[30:31] offset:84
	global_atomic_add v132, v133, s[30:31] offset:88
	global_atomic_add v132, v133, s[30:31] offset:92
	global_atomic_add v132, v133, s[30:31] offset:96
	global_atomic_add v132, v133, s[30:31] offset:100
	global_atomic_add v132, v133, s[30:31] offset:104
	global_atomic_add v132, v133, s[30:31] offset:108
	global_atomic_add v132, v133, s[30:31] offset:112
	global_atomic_add v132, v133, s[30:31] offset:116
	global_atomic_add v132, v133, s[30:31] offset:120
	global_atomic_add v132, v133, s[30:31] offset:124
	global_atomic_add v132, v133, s[30:31] offset:128
	global_atomic_add v132, v133, s[30:31] offset:132
	global_atomic_add v132, v133, s[30:31] offset:136
	global_atomic_add v132, v133, s[30:31] offset:140
	global_atomic_add v132, v133, s[30:31] offset:144
	global_atomic_add v132, v133, s[30:31] offset:148
	global_atomic_add v132, v133, s[30:31] offset:152
	global_atomic_add v132, v133, s[30:31] offset:156
	global_atomic_add v132, v133, s[30:31] offset:160
	global_atomic_add v132, v133, s[30:31] offset:164
	global_atomic_add v132, v133, s[30:31] offset:168
	global_atomic_add v132, v133, s[30:31] offset:172
	global_atomic_add v132, v133, s[30:31] offset:176
	global_atomic_add v132, v133, s[30:31] offset:180
	global_atomic_add v132, v133, s[30:31] offset:184
	global_atomic_add v132, v133, s[30:31] offset:188
	global_atomic_add v132, v133, s[30:31] offset:192
	global_atomic_add v132, v133, s[30:31] offset:196
	global_atomic_add v132, v133, s[30:31] offset:200
	global_atomic_add v132, v133, s[30:31] offset:204
	global_atomic_add v132, v133, s[30:31] offset:208
	global_atomic_add v132, v133, s[30:31] offset:212
	global_atomic_add v132, v133, s[30:31] offset:216
	global_atomic_add v132, v133, s[30:31] offset:220
	global_atomic_add v132, v133, s[30:31] offset:224
	global_atomic_add v132, v133, s[30:31] offset:228
	global_atomic_add v132, v133, s[30:31] offset:232
	global_atomic_add v132, v133, s[30:31] offset:236
	global_atomic_add v132, v133, s[30:31] offset:240
	global_atomic_add v132, v133, s[30:31] offset:244
	global_atomic_add v132, v133, s[30:31] offset:248
	global_atomic_add v132, v133, s[30:31] offset:252
.Llb_rep_done:
	s_mov_b64 exec, s[4:5]

.Lxb_done_2:
	s_or_b64 exec, exec, s[4:5]
	s_waitcnt lgkmcnt(0)
	s_barrier
	s_and_b32 s17, s78, 63
	s_lshl_b32 s17, s17, 2
	s_add_i32 s17, s17, 0x7fd00
	v_mov_b32_e32 v132, s17
	global_load_dword v132, v132, s[30:31] sc1
	s_waitcnt vmcnt(0)
	v_readfirstlane_b32 s17, v132
	v_writelane_b32 v250, s17, 60

.LBB0_1762:
	v_readlane_b32 s66, v251, 55
	v_readlane_b32 s67, v251, 56
	s_cmp_gt_i32 s67, 6
	s_cbranch_scc0 .LBB0_1812
	s_waitcnt vmcnt(0)
	s_waitcnt vmcnt(63) expcnt(7) lgkmcnt(15)
	s_barrier
	s_mov_b64 s[4:5], exec
	v_readlane_b32 s2, v251, 3
	v_readlane_b32 s3, v251, 4
	s_and_b64 s[2:3], s[4:5], s[2:3]
	s_mov_b64 exec, s[2:3]
	s_cbranch_execz .Lxb_done_6
	v_mov_b32_e32 v0, 0
	s_waitcnt vmcnt(0) expcnt(0) lgkmcnt(0)
	ds_read_b32 v2, v0
	ds_read_b32 v1, v0 offset:4
	v_readlane_b32 s0, v251, 2
	v_readlane_b32 s6, v251, 5
	v_readlane_b32 s7, v251, 6
	s_lshl_b32 s0, s0, 8
	s_add_u32 s8, s6, s0
	s_addc_u32 s9, s7, 0
	v_mov_b32_e32 v3, 1
	v_mov_b32_e32 v4, 0x1000
	s_nop 4
	global_atomic_add v3, v4, v3, s[8:9] offset:1024 sc0
	buffer_inv sc1
	s_sub_u32 s10, 5, s66
	s_add_u32 s11, s10, 1
	s_waitcnt lgkmcnt(0)
	v_readfirstlane_b32 s12, v2
	v_readfirstlane_b32 s13, v1
	s_mul_i32 s14, s12, s11
	s_mul_i32 s15, s13, s11
	s_waitcnt vmcnt(0)
	v_readfirstlane_b32 s16, v3
	s_add_u32 s16, s16, 1
	s_cmp_lg_u32 s16, s14
	s_cbranch_scc1 .Lxb_wait_6
	v_readlane_b32 s17, v250, 60
	s_cmp_lg_u32 s17, 0
	s_cbranch_scc1 .Lxb_glob_6
	s_waitcnt vmcnt(0)
	v_mov_b32_e32 v3, 1
	v_mov_b32_e32 v4, 0x7f000
	global_atomic_add v3, v4, v3, s[30:31] offset:1024 sc0
	s_waitcnt vmcnt(0)
	v_mov_b32_e32 v3, 1
	v_mov_b32_e32 v4, s0
	v_add_u32_e32 v4, 0x2400, v4
	global_atomic_add v4, v3, s[6:7]
	s_branch .Lxb_wait_6
.Lxb_glob_6:
	buffer_wbl2 sc1
	s_waitcnt vmcnt(0)
	v_mov_b32_e32 v3, 1
	v_mov_b32_e32 v4, 0x7f000
	global_atomic_add v3, v4, v3, s[30:31] offset:1024 sc0
	s_waitcnt vmcnt(0)
	v_readfirstlane_b32 s16, v3
	s_add_u32 s16, s16, 1
	s_cmp_lg_u32 s16, s15
	s_cbranch_scc1 .Lxb_wait_6
	v_mov_b32_e32 v3, 1
	v_mov_b32_e32 v4, 0x2400
	global_atomic_add v4, v3, s[6:7]
	v_add_u32_e32 v4, 0x100, v4
	global_atomic_add v4, v3, s[6:7]
	v_add_u32_e32 v4, 0x100, v4
	global_atomic_add v4, v3, s[6:7]
	v_add_u32_e32 v4, 0x100, v4
	global_atomic_add v4, v3, s[6:7]
	v_add_u32_e32 v4, 0x100, v4
	global_atomic_add v4, v3, s[6:7]
	v_add_u32_e32 v4, 0x100, v4
	global_atomic_add v4, v3, s[6:7]
	v_add_u32_e32 v4, 0x100, v4
	global_atomic_add v4, v3, s[6:7]
	v_add_u32_e32 v4, 0x100, v4
	global_atomic_add v4, v3, s[6:7]
	v_add_u32_e32 v4, 0x100, v4
	global_atomic_add v4, v3, s[6:7]
	v_add_u32_e32 v4, 0x100, v4
	global_atomic_add v4, v3, s[6:7]
	v_add_u32_e32 v4, 0x100, v4
	global_atomic_add v4, v3, s[6:7]
	v_add_u32_e32 v4, 0x100, v4
	global_atomic_add v4, v3, s[6:7]
	v_add_u32_e32 v4, 0x100, v4
	global_atomic_add v4, v3, s[6:7]
	v_add_u32_e32 v4, 0x100, v4
	global_atomic_add v4, v3, s[6:7]
	v_add_u32_e32 v4, 0x100, v4
	global_atomic_add v4, v3, s[6:7]
	v_add_u32_e32 v4, 0x100, v4
	global_atomic_add v4, v3, s[6:7]
	v_add_u32_e32 v4, 0x100, v4
	v_mov_b32_e32 v4, 0x7f000
	global_atomic_add v4, v3, s[30:31] offset:1280

.LBB0_1828:
	s_cmp_gt_i32 s67, 7
	s_cbranch_scc0 .LBB0_1878
	s_waitcnt vmcnt(0)
	s_waitcnt vmcnt(63) expcnt(7) lgkmcnt(15)
	s_barrier
	s_mov_b64 s[4:5], exec
	v_readlane_b32 s2, v251, 3
	v_readlane_b32 s3, v251, 4
	s_and_b64 s[2:3], s[4:5], s[2:3]
	s_mov_b64 exec, s[2:3]
	s_cbranch_execz .Lxb_done_7
	v_mov_b32_e32 v0, 0
	s_waitcnt vmcnt(0) expcnt(0) lgkmcnt(0)
	ds_read_b32 v2, v0
	ds_read_b32 v1, v0 offset:4
	v_readlane_b32 s0, v251, 2
	v_readlane_b32 s6, v251, 5
	v_readlane_b32 s7, v251, 6
	s_lshl_b32 s0, s0, 8
	s_add_u32 s8, s6, s0
	s_addc_u32 s9, s7, 0
	v_mov_b32_e32 v3, 1
	v_mov_b32_e32 v4, 0x1000
	s_nop 4
	global_atomic_add v3, v4, v3, s[8:9] offset:1024 sc0
	buffer_inv sc1
	s_sub_u32 s10, 6, s66
	s_add_u32 s11, s10, 1
	s_waitcnt lgkmcnt(0)
	v_readfirstlane_b32 s12, v2
	v_readfirstlane_b32 s13, v1
	s_mul_i32 s14, s12, s11
	s_mul_i32 s15, s13, s11
	s_waitcnt vmcnt(0)
	v_readfirstlane_b32 s16, v3
	s_add_u32 s16, s16, 1
	s_cmp_lg_u32 s16, s14
	s_cbranch_scc1 .Lxb_wait_7
	v_readlane_b32 s17, v250, 60
	s_cmp_lg_u32 s17, 0
	s_cbranch_scc1 .Lxb_glob_7
	s_waitcnt vmcnt(0)
	v_mov_b32_e32 v3, 1
	v_mov_b32_e32 v4, 0x7f000
	global_atomic_add v3, v4, v3, s[30:31] offset:1024 sc0
	s_waitcnt vmcnt(0)
	v_mov_b32_e32 v3, 1
	v_mov_b32_e32 v4, s0
	v_add_u32_e32 v4, 0x2400, v4
	global_atomic_add v4, v3, s[6:7]
	s_branch .Lxb_wait_7

.LBB0_1882:
	s_cmp_gt_u32 s67, 8
	s_cbranch_scc0 .LBB0_1932
	s_waitcnt vmcnt(0)
	s_waitcnt vmcnt(63) expcnt(7) lgkmcnt(15)
	s_barrier
	s_mov_b64 s[4:5], exec
	v_readlane_b32 s2, v251, 3
	v_readlane_b32 s3, v251, 4
	s_and_b64 s[2:3], s[4:5], s[2:3]
	s_mov_b64 exec, s[2:3]
	s_cbranch_execz .Lxb_done_8
	v_mov_b32_e32 v0, 0
	s_waitcnt vmcnt(0) expcnt(0) lgkmcnt(0)
	ds_read_b32 v2, v0
	ds_read_b32 v1, v0 offset:4
	v_readlane_b32 s0, v251, 2
	v_readlane_b32 s6, v251, 5
	v_readlane_b32 s7, v251, 6
	s_lshl_b32 s0, s0, 8
	s_add_u32 s8, s6, s0
	s_addc_u32 s9, s7, 0
	v_mov_b32_e32 v3, 1
	v_mov_b32_e32 v4, 0x1000
	s_nop 4
	global_atomic_add v3, v4, v3, s[8:9] offset:1024 sc0
	buffer_inv sc1
	s_sub_u32 s10, 7, s66
	s_add_u32 s11, s10, 1
	s_waitcnt lgkmcnt(0)
	v_readfirstlane_b32 s12, v2
	v_readfirstlane_b32 s13, v1
	s_mul_i32 s14, s12, s11
	s_mul_i32 s15, s13, s11
	s_waitcnt vmcnt(0)
	v_readfirstlane_b32 s16, v3
	s_add_u32 s16, s16, 1
	s_cmp_lg_u32 s16, s14
	s_cbranch_scc1 .Lxb_wait_8
	v_readlane_b32 s17, v250, 60
	s_cmp_lg_u32 s17, 0
	s_cbranch_scc1 .Lxb_glob_8
	s_waitcnt vmcnt(0)
	v_mov_b32_e32 v3, 1
	v_mov_b32_e32 v4, 0x7f000
	global_atomic_add v3, v4, v3, s[30:31] offset:1024 sc0
	s_waitcnt vmcnt(0)
	v_mov_b32_e32 v3, 1
	v_mov_b32_e32 v4, s0
	v_add_u32_e32 v4, 0x2400, v4
	global_atomic_add v4, v3, s[6:7]
	s_branch .Lxb_wait_8

.Lcv_ret_p4:
	s_mov_b32 s101, 0
	s_cmp_gt_i32 s67, 9
	s_cbranch_scc0 .LBB0_1992
	s_waitcnt vmcnt(0)
	s_waitcnt vmcnt(63) expcnt(7) lgkmcnt(15)
	s_barrier
	s_mov_b64 s[4:5], exec
	v_readlane_b32 s2, v251, 3
	v_readlane_b32 s3, v251, 4
	s_and_b64 s[2:3], s[4:5], s[2:3]
	s_mov_b64 exec, s[2:3]
	s_cbranch_execz .Lxb_done_9
	v_mov_b32_e32 v0, 0
	s_waitcnt vmcnt(0) expcnt(0) lgkmcnt(0)
	ds_read_b32 v2, v0
	ds_read_b32 v1, v0 offset:4
	v_readlane_b32 s0, v251, 2
	v_readlane_b32 s6, v251, 5
	v_readlane_b32 s7, v251, 6
	s_lshl_b32 s0, s0, 8
	s_add_u32 s8, s6, s0
	s_addc_u32 s9, s7, 0
	v_mov_b32_e32 v3, 1
	v_mov_b32_e32 v4, 0x1000
	s_nop 4
	global_atomic_add v3, v4, v3, s[8:9] offset:1024 sc0
	buffer_inv sc1
	s_sub_u32 s10, 8, s66
	s_add_u32 s11, s10, 1
	s_waitcnt lgkmcnt(0)
	v_readfirstlane_b32 s12, v2
	v_readfirstlane_b32 s13, v1
	s_mul_i32 s14, s12, s11
	s_mul_i32 s15, s13, s11
	s_waitcnt vmcnt(0)
	v_readfirstlane_b32 s16, v3
	s_add_u32 s16, s16, 1
	s_cmp_lg_u32 s16, s14
	s_cbranch_scc1 .Lxb_wait_9
	v_readlane_b32 s17, v250, 60
	s_cmp_lg_u32 s17, 0
	s_cbranch_scc1 .Lxb_glob_9
	s_waitcnt vmcnt(0)
	v_mov_b32_e32 v3, 1
	v_mov_b32_e32 v4, 0x7f000
	global_atomic_add v3, v4, v3, s[30:31] offset:1024 sc0
	s_waitcnt vmcnt(0)
	v_mov_b32_e32 v3, 1
	v_mov_b32_e32 v4, s0
	v_add_u32_e32 v4, 0x2400, v4
	global_atomic_add v4, v3, s[6:7]
	s_branch .Lxb_wait_9

.LBB0_2007:
	s_cmp_gt_i32 s67, 10
	s_cbranch_scc0 .LBB0_2057
	s_waitcnt vmcnt(0)
	s_waitcnt vmcnt(63) expcnt(7) lgkmcnt(15)
	s_barrier
	s_mov_b64 s[4:5], exec
	v_readlane_b32 s2, v251, 3
	v_readlane_b32 s3, v251, 4
	s_and_b64 s[2:3], s[4:5], s[2:3]
	s_mov_b64 exec, s[2:3]
	s_cbranch_execz .Lxb_done_10
	v_mov_b32_e32 v0, 0
	s_waitcnt vmcnt(0) expcnt(0) lgkmcnt(0)
	ds_read_b32 v2, v0
	ds_read_b32 v1, v0 offset:4
	v_readlane_b32 s0, v251, 2
	v_readlane_b32 s6, v251, 5
	v_readlane_b32 s7, v251, 6
	s_lshl_b32 s0, s0, 8
	s_add_u32 s8, s6, s0
	s_addc_u32 s9, s7, 0
	v_mov_b32_e32 v3, 1
	v_mov_b32_e32 v4, 0x1000
	s_nop 4
	global_atomic_add v3, v4, v3, s[8:9] offset:1024 sc0
	buffer_inv sc1
	s_sub_u32 s10, 9, s66
	s_add_u32 s11, s10, 1
	s_waitcnt lgkmcnt(0)
	v_readfirstlane_b32 s12, v2
	v_readfirstlane_b32 s13, v1
	s_mul_i32 s14, s12, s11
	s_mul_i32 s15, s13, s11
	s_waitcnt vmcnt(0)
	v_readfirstlane_b32 s16, v3
	s_add_u32 s16, s16, 1
	s_cmp_lg_u32 s16, s14
	s_cbranch_scc1 .Lxb_wait_10
	v_readlane_b32 s17, v250, 60
	s_cmp_lg_u32 s17, 0
	s_cbranch_scc1 .Lxb_glob_10
	s_waitcnt vmcnt(0)
	v_mov_b32_e32 v3, 1
	v_mov_b32_e32 v4, 0x7f000
	global_atomic_add v3, v4, v3, s[30:31] offset:1024 sc0
	s_waitcnt vmcnt(0)
	v_mov_b32_e32 v3, 1
	v_mov_b32_e32 v4, s0
	v_add_u32_e32 v4, 0x2400, v4
	global_atomic_add v4, v3, s[6:7]
	s_branch .Lxb_wait_10

.LBB0_2127:
	s_cmp_gt_u32 s67, 12
	s_cbranch_scc0 .LBB0_2177
	s_waitcnt vmcnt(0)
	s_waitcnt vmcnt(63) expcnt(7) lgkmcnt(15)
	s_barrier
	s_mov_b64 s[4:5], exec
	v_readlane_b32 s2, v251, 3
	v_readlane_b32 s3, v251, 4
	s_and_b64 s[2:3], s[4:5], s[2:3]
	s_mov_b64 exec, s[2:3]
	s_cbranch_execz .Lxb_done_12
	v_mov_b32_e32 v0, 0
	s_waitcnt vmcnt(0) expcnt(0) lgkmcnt(0)
	ds_read_b32 v2, v0
	ds_read_b32 v1, v0 offset:4
	v_readlane_b32 s0, v251, 2
	v_readlane_b32 s6, v251, 5
	v_readlane_b32 s7, v251, 6
	s_lshl_b32 s0, s0, 8
	s_add_u32 s8, s6, s0
	s_addc_u32 s9, s7, 0
	v_mov_b32_e32 v3, 1
	v_mov_b32_e32 v4, 0x1000
	s_nop 4
	global_atomic_add v3, v4, v3, s[8:9] offset:1024 sc0
	buffer_inv sc1
	s_sub_u32 s10, 11, s66
	s_add_u32 s11, s10, 1
	s_waitcnt lgkmcnt(0)
	v_readfirstlane_b32 s12, v2
	v_readfirstlane_b32 s13, v1
	s_mul_i32 s14, s12, s11
	s_mul_i32 s15, s13, s11
	s_waitcnt vmcnt(0)
	v_readfirstlane_b32 s16, v3
	s_add_u32 s16, s16, 1
	s_cmp_lg_u32 s16, s14
	s_cbranch_scc1 .Lxb_wait_12
	v_readlane_b32 s17, v250, 60
	s_cmp_lg_u32 s17, 0
	s_cbranch_scc1 .Lxb_glob_12
	s_waitcnt vmcnt(0)
	v_mov_b32_e32 v3, 1
	v_mov_b32_e32 v4, 0x7f000
	global_atomic_add v3, v4, v3, s[30:31] offset:1024 sc0
	s_waitcnt vmcnt(0)
	v_mov_b32_e32 v3, 1
	v_mov_b32_e32 v4, s0
	v_add_u32_e32 v4, 0x2400, v4
	global_atomic_add v4, v3, s[6:7]
	s_branch .Lxb_wait_12

.LBB0_3751:
	s_cmp_gt_i32 s67, 16
	s_cbranch_scc0 .LBB0_3801
	s_waitcnt vmcnt(0)
	s_waitcnt vmcnt(63) expcnt(7) lgkmcnt(15)
	s_barrier
	s_mov_b64 s[4:5], exec
	v_readlane_b32 s2, v251, 3
	v_readlane_b32 s3, v251, 4
	s_and_b64 s[2:3], s[4:5], s[2:3]
	s_mov_b64 exec, s[2:3]
	s_cbranch_execz .Lxb_done_16
	v_mov_b32_e32 v0, 0
	s_waitcnt vmcnt(0) expcnt(0) lgkmcnt(0)
	ds_read_b32 v2, v0
	ds_read_b32 v1, v0 offset:4
	v_readlane_b32 s0, v251, 2
	v_readlane_b32 s6, v251, 5
	v_readlane_b32 s7, v251, 6
	s_lshl_b32 s0, s0, 8
	s_add_u32 s8, s6, s0
	s_addc_u32 s9, s7, 0
	v_mov_b32_e32 v3, 1
	v_mov_b32_e32 v4, 0x1000
	s_nop 4
	global_atomic_add v3, v4, v3, s[8:9] offset:1024 sc0
	buffer_inv sc1
	s_sub_u32 s10, 15, s66
	s_add_u32 s11, s10, 1
	s_waitcnt lgkmcnt(0)
	v_readfirstlane_b32 s12, v2
	v_readfirstlane_b32 s13, v1
	s_mul_i32 s14, s12, s11
	s_mul_i32 s15, s13, s11
	s_waitcnt vmcnt(0)
	v_readfirstlane_b32 s16, v3
	s_add_u32 s16, s16, 1
	s_cmp_lg_u32 s16, s14
	s_cbranch_scc1 .Lxb_wait_16
	v_readlane_b32 s17, v250, 60
	s_cmp_lg_u32 s17, 0
	s_cbranch_scc1 .Lxb_glob_16
	s_waitcnt vmcnt(0)
	v_mov_b32_e32 v3, 1
	v_mov_b32_e32 v4, 0x7f000
	global_atomic_add v3, v4, v3, s[30:31] offset:1024 sc0
	s_waitcnt vmcnt(0)
	v_mov_b32_e32 v3, 1
	v_mov_b32_e32 v4, s0
	v_add_u32_e32 v4, 0x2400, v4
	global_atomic_add v4, v3, s[6:7]
	s_branch .Lxb_wait_16

.LBB0_3817:
	s_cmp_gt_i32 s67, 17
	s_cbranch_scc0 .LBB0_3867
	s_waitcnt vmcnt(0)
	s_waitcnt vmcnt(63) expcnt(7) lgkmcnt(15)
	s_barrier
	s_mov_b64 s[4:5], exec
	v_readlane_b32 s2, v251, 3
	v_readlane_b32 s3, v251, 4
	s_and_b64 s[2:3], s[4:5], s[2:3]
	s_mov_b64 exec, s[2:3]
	s_cbranch_execz .Lxb_done_17
	v_mov_b32_e32 v0, 0
	s_waitcnt vmcnt(0) expcnt(0) lgkmcnt(0)
	ds_read_b32 v2, v0
	ds_read_b32 v1, v0 offset:4
	v_readlane_b32 s0, v251, 2
	v_readlane_b32 s6, v251, 5
	v_readlane_b32 s7, v251, 6
	s_lshl_b32 s0, s0, 8
	s_add_u32 s8, s6, s0
	s_addc_u32 s9, s7, 0
	v_mov_b32_e32 v3, 1
	v_mov_b32_e32 v4, 0x1000
	s_nop 4
	global_atomic_add v3, v4, v3, s[8:9] offset:1024 sc0
	buffer_inv sc1
	s_sub_u32 s10, 16, s66
	s_add_u32 s11, s10, 1
	s_waitcnt lgkmcnt(0)
	v_readfirstlane_b32 s12, v2
	v_readfirstlane_b32 s13, v1
	s_mul_i32 s14, s12, s11
	s_mul_i32 s15, s13, s11
	s_waitcnt vmcnt(0)
	v_readfirstlane_b32 s16, v3
	s_add_u32 s16, s16, 1
	s_cmp_lg_u32 s16, s14
	s_cbranch_scc1 .Lxb_wait_17
	v_readlane_b32 s17, v250, 60
	s_cmp_lg_u32 s17, 0
	s_cbranch_scc1 .Lxb_glob_17
	s_waitcnt vmcnt(0)
	v_mov_b32_e32 v3, 1
	v_mov_b32_e32 v4, 0x7f000
	global_atomic_add v3, v4, v3, s[30:31] offset:1024 sc0
	s_waitcnt vmcnt(0)
	v_mov_b32_e32 v3, 1
	v_mov_b32_e32 v4, s0
	v_add_u32_e32 v4, 0x2400, v4
	global_atomic_add v4, v3, s[6:7]
	s_branch .Lxb_wait_17

.LBB0_3871:
	s_cmp_gt_u32 s67, 18
	s_cbranch_scc0 .LBB0_3921
	s_waitcnt vmcnt(0)
	s_waitcnt vmcnt(63) expcnt(7) lgkmcnt(15)
	s_barrier
	s_mov_b64 s[4:5], exec
	v_readlane_b32 s2, v251, 3
	v_readlane_b32 s3, v251, 4
	s_and_b64 s[2:3], s[4:5], s[2:3]
	s_mov_b64 exec, s[2:3]
	s_cbranch_execz .Lxb_done_18
	v_mov_b32_e32 v0, 0
	s_waitcnt vmcnt(0) expcnt(0) lgkmcnt(0)
	ds_read_b32 v2, v0
	ds_read_b32 v1, v0 offset:4
	v_readlane_b32 s0, v251, 2
	v_readlane_b32 s6, v251, 5
	v_readlane_b32 s7, v251, 6
	s_lshl_b32 s0, s0, 8
	s_add_u32 s8, s6, s0
	s_addc_u32 s9, s7, 0
	v_mov_b32_e32 v3, 1
	v_mov_b32_e32 v4, 0x1000
	s_nop 4
	global_atomic_add v3, v4, v3, s[8:9] offset:1024 sc0
	buffer_inv sc1
	s_sub_u32 s10, 17, s66
	s_add_u32 s11, s10, 1
	s_waitcnt lgkmcnt(0)
	v_readfirstlane_b32 s12, v2
	v_readfirstlane_b32 s13, v1
	s_mul_i32 s14, s12, s11
	s_mul_i32 s15, s13, s11
	s_waitcnt vmcnt(0)
	v_readfirstlane_b32 s16, v3
	s_add_u32 s16, s16, 1
	s_cmp_lg_u32 s16, s14
	s_cbranch_scc1 .Lxb_wait_18
	v_readlane_b32 s17, v250, 60
	s_cmp_lg_u32 s17, 0
	s_cbranch_scc1 .Lxb_glob_18
	s_waitcnt vmcnt(0)
	v_mov_b32_e32 v3, 1
	v_mov_b32_e32 v4, 0x7f000
	global_atomic_add v3, v4, v3, s[30:31] offset:1024 sc0
	s_waitcnt vmcnt(0)
	v_mov_b32_e32 v3, 1
	v_mov_b32_e32 v4, s0
	v_add_u32_e32 v4, 0x2400, v4
	global_atomic_add v4, v3, s[6:7]
	s_branch .Lxb_wait_18

.LBB0_3931:
	s_cmp_gt_i32 s67, 19
	s_cbranch_scc0 .LBB0_3981
	s_waitcnt vmcnt(0)
	s_waitcnt vmcnt(63) expcnt(7) lgkmcnt(15)
	s_barrier
	s_mov_b64 s[4:5], exec
	v_readlane_b32 s2, v251, 3
	v_readlane_b32 s3, v251, 4
	s_and_b64 s[2:3], s[4:5], s[2:3]
	s_mov_b64 exec, s[2:3]
	s_cbranch_execz .Lxb_done_19
	v_mov_b32_e32 v0, 0
	s_waitcnt vmcnt(0) expcnt(0) lgkmcnt(0)
	ds_read_b32 v2, v0
	ds_read_b32 v1, v0 offset:4
	v_readlane_b32 s0, v251, 2
	v_readlane_b32 s6, v251, 5
	v_readlane_b32 s7, v251, 6
	s_lshl_b32 s0, s0, 8
	s_add_u32 s8, s6, s0
	s_addc_u32 s9, s7, 0
	v_mov_b32_e32 v3, 1
	v_mov_b32_e32 v4, 0x1000
	s_nop 4
	global_atomic_add v3, v4, v3, s[8:9] offset:1024 sc0
	buffer_inv sc1
	s_sub_u32 s10, 18, s66
	s_add_u32 s11, s10, 1
	s_waitcnt lgkmcnt(0)
	v_readfirstlane_b32 s12, v2
	v_readfirstlane_b32 s13, v1
	s_mul_i32 s14, s12, s11
	s_mul_i32 s15, s13, s11
	s_waitcnt vmcnt(0)
	v_readfirstlane_b32 s16, v3
	s_add_u32 s16, s16, 1
	s_cmp_lg_u32 s16, s14
	s_cbranch_scc1 .Lxb_wait_19
	v_readlane_b32 s17, v250, 60
	s_cmp_lg_u32 s17, 0
	s_cbranch_scc1 .Lxb_glob_19
	s_waitcnt vmcnt(0)
	v_mov_b32_e32 v3, 1
	v_mov_b32_e32 v4, 0x7f000
	global_atomic_add v3, v4, v3, s[30:31] offset:1024 sc0
	s_waitcnt vmcnt(0)
	v_mov_b32_e32 v3, 1
	v_mov_b32_e32 v4, s0
	v_add_u32_e32 v4, 0x2400, v4
	global_atomic_add v4, v3, s[6:7]
	s_branch .Lxb_wait_19

.LBB0_3996:
	s_cmp_gt_i32 s67, 20
	s_cbranch_scc0 .LBB0_4046
	s_waitcnt vmcnt(0)
	s_waitcnt vmcnt(63) expcnt(7) lgkmcnt(15)
	s_barrier
	s_mov_b64 s[4:5], exec
	v_readlane_b32 s2, v251, 3
	v_readlane_b32 s3, v251, 4
	s_and_b64 s[2:3], s[4:5], s[2:3]
	s_mov_b64 exec, s[2:3]
	s_cbranch_execz .Lxb_done_20
	v_mov_b32_e32 v0, 0
	s_waitcnt vmcnt(0) expcnt(0) lgkmcnt(0)
	ds_read_b32 v2, v0
	ds_read_b32 v1, v0 offset:4
	v_readlane_b32 s0, v251, 2
	v_readlane_b32 s6, v251, 5
	v_readlane_b32 s7, v251, 6
	s_lshl_b32 s0, s0, 8
	s_add_u32 s8, s6, s0
	s_addc_u32 s9, s7, 0
	v_mov_b32_e32 v3, 1
	v_mov_b32_e32 v4, 0x1000
	s_nop 4
	global_atomic_add v3, v4, v3, s[8:9] offset:1024 sc0
	buffer_inv sc1
	s_sub_u32 s10, 19, s66
	s_add_u32 s11, s10, 1
	s_waitcnt lgkmcnt(0)
	v_readfirstlane_b32 s12, v2
	v_readfirstlane_b32 s13, v1
	s_mul_i32 s14, s12, s11
	s_mul_i32 s15, s13, s11
	s_waitcnt vmcnt(0)
	v_readfirstlane_b32 s16, v3
	s_add_u32 s16, s16, 1
	s_cmp_lg_u32 s16, s14
	s_cbranch_scc1 .Lxb_wait_20
	v_readlane_b32 s17, v250, 60
	s_cmp_lg_u32 s17, 0
	s_cbranch_scc1 .Lxb_glob_20
	s_waitcnt vmcnt(0)
	v_mov_b32_e32 v3, 1
	v_mov_b32_e32 v4, 0x7f000
	global_atomic_add v3, v4, v3, s[30:31] offset:1024 sc0
	s_waitcnt vmcnt(0)
	v_mov_b32_e32 v3, 1
	v_mov_b32_e32 v4, s0
	v_add_u32_e32 v4, 0x2400, v4
	global_atomic_add v4, v3, s[6:7]
	s_branch .Lxb_wait_20
